# FFN-down residual epilogue: wait for the previous row group's stores before issuing the next group's loads (read and write bursts separated, as the mixer epilogue does); on top of v50
# speedup vs baseline: 1.0039x; 1.0039x over previous
.LBB0_1256:
	v_add_u32_e32 v186, 0x80, v166
	v_ashrrev_i32_e32 v187, 31, v186
	v_lshlrev_b64 v[204:205], 12, v[186:187]
	v_add_u32_e32 v164, 0x90, v166
	v_add_u32_e32 v172, 0xa0, v166
	v_add_u32_e32 v220, 0xb0, v166
	v_lshl_add_u64 v[214:215], v[170:171], 0, v[204:205]
	v_ashrrev_i32_e32 v165, 31, v164
	v_ashrrev_i32_e32 v173, 31, v172
	v_ashrrev_i32_e32 v221, 31, v220
	s_waitcnt vmcnt(0)
	v_lshl_add_u64 v[246:247], v[214:215], 0, s[98:99]
	flat_load_dwordx4 v[182:185], v[246:247]
	v_lshlrev_b64 v[206:207], 12, v[164:165]
	v_lshlrev_b64 v[208:209], 12, v[172:173]
	v_lshlrev_b64 v[210:211], 12, v[220:221]
	v_lshl_add_u64 v[174:175], v[170:171], 0, v[206:207]
	v_lshl_add_u64 v[222:223], v[170:171], 0, v[208:209]
	v_lshl_add_u64 v[218:219], v[170:171], 0, v[210:211]
	v_lshl_add_u64 v[246:247], v[174:175], 0, s[98:99]
	flat_load_dwordx4 v[130:133], v[246:247]
	v_lshl_add_u64 v[246:247], v[222:223], 0, s[98:99]
	flat_load_dwordx4 v[126:129], v[246:247]
	v_lshl_add_u64 v[246:247], v[218:219], 0, s[98:99]
	flat_load_dwordx4 v[122:125], v[246:247]
	v_lshlrev_b64 v[212:213], 11, v[186:187]
	v_lshl_add_u64 v[170:171], v[212:213], 0, v[176:177]
	s_and_b64 vcc, exec, s[8:9]
	s_waitcnt vmcnt(0) lgkmcnt(0)
	v_lshlrev_b32_e32 v216, 16, v182
	v_and_b32_e32 v217, 0xffff0000, v182
	v_lshlrev_b32_e32 v182, 16, v183
	v_and_b32_e32 v183, 0xffff0000, v183
	v_lshlrev_b32_e32 v230, 16, v184
	v_and_b32_e32 v231, 0xffff0000, v184
	v_lshlrev_b32_e32 v184, 16, v185
	v_and_b32_e32 v185, 0xffff0000, v185
	v_pk_mul_f32 v[182:183], v[182:183], v[234:235]
	v_pk_fma_f32 v[120:121], v[120:121], v[112:113], v[182:183]
	v_pk_mul_f32 v[216:217], v[216:217], v[232:233]
	v_pk_fma_f32 v[118:119], v[118:119], v[110:111], v[216:217]
	v_pk_mul_f32 v[230:231], v[230:231], v[240:241]
	v_pk_fma_f32 v[114:115], v[114:115], v[106:107], v[230:231]
	v_pk_mul_f32 v[184:185], v[184:185], v[242:243]
	v_pk_fma_f32 v[116:117], v[116:117], v[108:109], v[184:185]
	v_cvt_pk_bf16_f32 v182, v118, v119
	v_cvt_pk_bf16_f32 v183, v120, v121
	v_cvt_pk_bf16_f32 v184, v114, v115
	s_nop 0
	v_cvt_pk_bf16_f32 v185, v116, v117
	s_cbranch_vccz .Lxs2_5
	flat_store_dwordx4 v[214:215], v[182:185]

.LBB0_1276:
	v_ashrrev_i32_e32 v103, 31, v102
	v_lshl_add_u64 v[90:91], s[12:13], 0, v[188:189]
	v_lshlrev_b64 v[104:105], 1, v[102:103]
	v_lshl_add_u64 v[186:187], v[90:91], 0, v[104:105]
	v_lshl_add_u64 v[90:91], s[12:13], 0, v[190:191]
	s_waitcnt vmcnt(0)
	v_lshl_add_u64 v[246:247], v[186:187], 0, s[98:99]
	flat_load_dwordx4 v[182:185], v[246:247]
	v_lshl_add_u64 v[92:93], s[12:13], 0, v[192:193]
	v_lshl_add_u64 v[94:95], s[12:13], 0, v[194:195]
	v_lshl_add_u64 v[178:179], v[90:91], 0, v[104:105]
	v_lshl_add_u64 v[176:177], v[92:93], 0, v[104:105]
	v_lshl_add_u64 v[124:125], v[94:95], 0, v[104:105]
	v_lshl_add_u64 v[246:247], v[178:179], 0, s[98:99]
	flat_load_dwordx4 v[98:101], v[246:247]
	v_lshl_add_u64 v[246:247], v[176:177], 0, s[98:99]
	flat_load_dwordx4 v[94:97], v[246:247]
	v_lshl_add_u64 v[246:247], v[124:125], 0, s[98:99]
	flat_load_dwordx4 v[90:93], v[246:247]
	v_lshl_add_u64 v[188:189], v[196:197], 0, v[102:103]
	s_and_b64 vcc, exec, s[8:9]
	s_waitcnt vmcnt(0) lgkmcnt(0)
	v_rcp_f32_e32 v232, v232
	v_rcp_f32_e32 v233, v233
	v_rcp_f32_e32 v234, v234
	v_rcp_f32_e32 v235, v235
	v_rcp_f32_e32 v240, v240
	v_rcp_f32_e32 v241, v241
	v_rcp_f32_e32 v242, v242
	v_rcp_f32_e32 v243, v243
	s_nop 0
	v_lshlrev_b32_e32 v190, 16, v182
	v_and_b32_e32 v191, 0xffff0000, v182
	v_lshlrev_b32_e32 v182, 16, v183
	v_and_b32_e32 v183, 0xffff0000, v183
	v_lshlrev_b32_e32 v192, 16, v184
	v_and_b32_e32 v193, 0xffff0000, v184
	v_lshlrev_b32_e32 v184, 16, v185
	v_and_b32_e32 v185, 0xffff0000, v185
	v_pk_mul_f32 v[182:183], v[182:183], v[234:235]
	v_pk_fma_f32 v[64:65], v[64:65], v[88:89], v[182:183]
	v_pk_mul_f32 v[190:191], v[190:191], v[232:233]
	v_pk_fma_f32 v[62:63], v[62:63], v[86:87], v[190:191]
	v_pk_mul_f32 v[192:193], v[192:193], v[240:241]
	v_pk_fma_f32 v[58:59], v[58:59], v[82:83], v[192:193]
	v_pk_mul_f32 v[184:185], v[184:185], v[242:243]
	v_pk_fma_f32 v[60:61], v[60:61], v[84:85], v[184:185]
	v_cvt_pk_bf16_f32 v182, v62, v63
	v_cvt_pk_bf16_f32 v183, v64, v65
	v_cvt_pk_bf16_f32 v184, v58, v59
	s_nop 0
	v_cvt_pk_bf16_f32 v185, v60, v61
	s_cbranch_vccz .Lxs2_9
	flat_store_dwordx4 v[186:187], v[182:185]

.LBB0_1292:
	s_nop 1
	v_lshl_add_u64 v[34:35], s[12:13], 0, v[204:205]
	v_lshl_add_u64 v[186:187], v[34:35], 0, v[104:105]
	v_lshl_add_u64 v[34:35], s[12:13], 0, v[206:207]
	s_waitcnt vmcnt(0)
	v_lshl_add_u64 v[246:247], v[186:187], 0, s[98:99]
	flat_load_dwordx4 v[182:185], v[246:247]
	v_lshl_add_u64 v[36:37], s[12:13], 0, v[208:209]
	v_lshl_add_u64 v[38:39], s[12:13], 0, v[210:211]
	v_lshl_add_u64 v[176:177], v[34:35], 0, v[104:105]
	v_lshl_add_u64 v[124:125], v[36:37], 0, v[104:105]
	v_lshl_add_u64 v[104:105], v[38:39], 0, v[104:105]
	v_lshl_add_u64 v[246:247], v[176:177], 0, s[98:99]
	flat_load_dwordx4 v[42:45], v[246:247]
	v_lshl_add_u64 v[246:247], v[124:125], 0, s[98:99]
	flat_load_dwordx4 v[38:41], v[246:247]
	v_lshl_add_u64 v[246:247], v[104:105], 0, s[98:99]
	flat_load_dwordx4 v[34:37], v[246:247]
	v_lshl_add_u64 v[178:179], v[212:213], 0, v[102:103]
	s_and_b64 vcc, exec, s[8:9]
	s_waitcnt vmcnt(0) lgkmcnt(0)
	v_lshlrev_b32_e32 v188, 16, v182
	v_and_b32_e32 v189, 0xffff0000, v182
	v_lshlrev_b32_e32 v182, 16, v183
	v_and_b32_e32 v183, 0xffff0000, v183
	v_lshlrev_b32_e32 v190, 16, v184
	v_and_b32_e32 v191, 0xffff0000, v184
	v_lshlrev_b32_e32 v184, 16, v185
	v_and_b32_e32 v185, 0xffff0000, v185
	v_pk_mul_f32 v[182:183], v[182:183], v[234:235]
	v_pk_fma_f32 v[32:33], v[32:33], v[88:89], v[182:183]
	v_pk_mul_f32 v[188:189], v[188:189], v[232:233]
	v_pk_fma_f32 v[30:31], v[30:31], v[86:87], v[188:189]
	v_pk_mul_f32 v[190:191], v[190:191], v[240:241]
	v_pk_fma_f32 v[26:27], v[26:27], v[82:83], v[190:191]
	v_pk_mul_f32 v[184:185], v[184:185], v[242:243]
	v_pk_fma_f32 v[28:29], v[28:29], v[84:85], v[184:185]
	v_cvt_pk_bf16_f32 v182, v30, v31
	v_cvt_pk_bf16_f32 v183, v32, v33
	v_cvt_pk_bf16_f32 v184, v26, v27
	s_nop 0
	v_cvt_pk_bf16_f32 v185, v28, v29
	s_cbranch_vccz .Lxs2_13
	flat_store_dwordx4 v[186:187], v[182:185]
